# grid barrier: the XCD leader's acquire invalidate also issued early (right after its write-back), before polling the cross-XCD release
# baseline (speedup 1.0000x reference)
.LBB0_68:
	s_andn2_saveexec_b64 s[0:1], s[8:9]
	s_cbranch_execz .LBB0_88
	s_mov_b64 s[8:9], exec
	buffer_wbl2 sc1
	s_waitcnt lgkmcnt(0)
	s_waitcnt vmcnt(0)
	buffer_inv sc1
	v_mbcnt_lo_u32_b32 v1, s8, 0
	v_mbcnt_hi_u32_b32 v1, s9, v1
	v_cmp_eq_u32_e32 vcc, 0, v1
	s_and_saveexec_b64 s[12:13], vcc
	s_cbranch_execz .LBB0_71
	s_bcnt1_i32_b64 s0, s[8:9]
	v_mov_b32_e32 v2, s0
	v_readlane_b32 s0, v255, 18
	v_readlane_b32 s1, v255, 19
	s_nop 4
	global_atomic_add v2, v197, v2, s[0:1] sc0

.LBB0_85:
	s_or_b64 exec, exec, s[8:9]
	s_mov_b64 s[8:9], exec
	v_mbcnt_lo_u32_b32 v0, s8, 0
	v_mbcnt_hi_u32_b32 v0, s9, v0
	v_cmp_eq_u32_e32 vcc, 0, v0
	s_waitcnt vmcnt(0)
	s_and_saveexec_b64 s[12:13], vcc
	s_cbranch_execz .LBB0_87
	s_bcnt1_i32_b64 s0, s[8:9]
	v_mov_b32_e32 v0, s0
	v_readlane_b32 s0, v255, 16
	v_readlane_b32 s1, v255, 17
	s_nop 4
	global_atomic_add v197, v0, s[0:1]

.LBB0_1105:
	s_mov_b64 s[8:9], exec
	buffer_wbl2 sc1
	s_waitcnt lgkmcnt(0)
	s_waitcnt vmcnt(0)
	buffer_inv sc1
	v_mbcnt_lo_u32_b32 v1, s8, 0
	v_mbcnt_hi_u32_b32 v1, s9, v1
	v_cmp_eq_u32_e32 vcc, 0, v1
	s_and_saveexec_b64 s[12:13], vcc
	s_cbranch_execz .LBB0_1107
	s_bcnt1_i32_b64 s0, s[8:9]
	v_mov_b32_e32 v2, s0
	v_readlane_b32 s0, v255, 18
	v_readlane_b32 s1, v255, 19
	s_nop 4
	global_atomic_add v2, v197, v2, s[0:1] sc0

.LBB0_1121:
	s_or_b64 exec, exec, s[8:9]
	s_mov_b64 s[8:9], exec
	v_mbcnt_lo_u32_b32 v0, s8, 0
	v_mbcnt_hi_u32_b32 v0, s9, v0
	v_cmp_eq_u32_e32 vcc, 0, v0
	s_waitcnt vmcnt(0)
	s_and_saveexec_b64 s[12:13], vcc
	s_cbranch_execnz .LBB0_1122
	s_getpc_b64 s[98:99]
